# grid barrier one-hop release: last cross-XCC arriver bumps every XCC generation word itself (no TOPGEN hop via XCC leaders)
# speedup vs baseline: 1.0084x; 1.0068x over previous
.LBB0_649:
	v_readlane_b32 s6, v253, 50
	s_add_u32 s57, s4, s6
	s_addc_u32 s56, s5, 0
	v_mov_b32_e32 v1, s57
	v_add_co_u32_e32 v4, vcc, 0x1000, v1
	v_mov_b32_e32 v1, s56
	s_nop 0
	v_addc_co_u32_e32 v5, vcc, 0, v1, vcc
	flat_atomic_add v3, v[4:5], v202 offset:1024 sc0
	v_cvt_f32_u32_e32 v1, v2
	v_sub_u32_e32 v4, 0, v2
	v_rcp_iflag_f32_e32 v1, v1
	s_nop 0
	v_mul_f32_e32 v1, 0x4f7ffffe, v1
	v_cvt_u32_f32_e32 v1, v1
	v_mul_lo_u32 v4, v4, v1
	v_mul_hi_u32 v4, v1, v4
	v_add_u32_e32 v1, v1, v4
	s_waitcnt vmcnt(0) lgkmcnt(0)
	v_mul_hi_u32 v1, v3, v1
	v_mul_lo_u32 v4, v1, v2
	v_sub_u32_e32 v4, v3, v4
	v_cmp_ge_u32_e32 vcc, v4, v2
	v_add_u32_e32 v5, 1, v1
	s_nop 0
	v_cndmask_b32_e32 v1, v1, v5, vcc
	v_sub_u32_e32 v5, v4, v2
	v_cndmask_b32_e32 v4, v4, v5, vcc
	v_cmp_ge_u32_e32 vcc, v4, v2
	v_add_u32_e32 v4, 1, v1
	s_nop 0
	v_cndmask_b32_e32 v1, v1, v4, vcc
	v_add_u32_e32 v4, 1, v3
	v_mad_u64_u32 v[2:3], s[6:7], v2, v1, v[2:3]
	v_cmp_ne_u32_e32 vcc, v4, v2
	s_cbranch_vccnz .Lgb_spin
	s_lshr_b32 s98, 0x160580, s14
	s_and_b32 s98, s98, 1
	v_readlane_b32 s99, v255, 59
	s_and_b32 s98, s98, s99
	s_cmp_eq_u32 s98, 1
	s_cbranch_scc1 .Lwb_skip
	buffer_wbl2 sc1
.Lwb_skip:
	s_waitcnt vmcnt(0)
	s_add_u32 s6, s4, 0x3000
	s_addc_u32 s7, s5, 0
	v_mov_b64_e32 v[20:21], s[6:7]
	flat_atomic_add v22, v[20:21], v202 offset:1024 sc0
	v_cvt_f32_u32_e32 v23, v0
	v_sub_u32_e32 v24, 0, v0
	v_rcp_iflag_f32_e32 v23, v23
	s_nop 0
	v_mul_f32_e32 v23, 0x4f7ffffe, v23
	v_cvt_u32_f32_e32 v23, v23
	v_mul_lo_u32 v24, v24, v23
	v_mul_hi_u32 v24, v23, v24
	v_add_u32_e32 v23, v23, v24
	s_waitcnt vmcnt(0) lgkmcnt(0)
	v_mul_hi_u32 v23, v22, v23
	v_mul_lo_u32 v24, v23, v0
	v_sub_u32_e32 v24, v22, v24
	v_cmp_ge_u32_e32 vcc, v24, v0
	v_add_u32_e32 v25, 1, v23
	s_nop 0
	v_cndmask_b32_e32 v23, v23, v25, vcc
	v_sub_u32_e32 v25, v24, v0
	v_cndmask_b32_e32 v24, v24, v25, vcc
	v_cmp_ge_u32_e32 vcc, v24, v0
	v_add_u32_e32 v24, 1, v23
	s_nop 0
	v_cndmask_b32_e32 v23, v23, v24, vcc
	v_add_u32_e32 v24, 1, v22
	v_mad_u64_u32 v[26:27], s[6:7], v0, v23, v[0:1]
	s_nop 0
	v_cmp_ne_u32_e32 vcc, v24, v26
	s_cbranch_vccnz .Lgb_spin
	s_add_u32 s6, s4, 0x2400
	s_addc_u32 s7, s5, 0
	v_mov_b64_e32 v[20:21], s[6:7]
	flat_atomic_add v[20:21], v202
	flat_atomic_add v[20:21], v202 offset:256
	flat_atomic_add v[20:21], v202 offset:512
	flat_atomic_add v[20:21], v202 offset:768
	flat_atomic_add v[20:21], v202 offset:1024
	flat_atomic_add v[20:21], v202 offset:1280
	flat_atomic_add v[20:21], v202 offset:1536
	flat_atomic_add v[20:21], v202 offset:1792
	flat_atomic_add v[20:21], v202 offset:2048
	flat_atomic_add v[20:21], v202 offset:2304
	flat_atomic_add v[20:21], v202 offset:2560
	flat_atomic_add v[20:21], v202 offset:2816
	flat_atomic_add v[20:21], v202 offset:3072
	flat_atomic_add v[20:21], v202 offset:3328
	flat_atomic_add v[20:21], v202 offset:3584
	flat_atomic_add v[20:21], v202 offset:3840
	s_branch .Lgb_acq

.Lgb_spin:
	s_add_u32 s10, s57, 0x2400
	s_addc_u32 s11, s56, 0
	v_mov_b64_e32 v[20:21], s[10:11]
	s_mov_b32 s58, 0
.Lgb_spin_loop:
	flat_load_dword v22, v[20:21] sc1
	s_waitcnt vmcnt(0) lgkmcnt(0)
	v_cmp_ne_u32_e32 vcc, v22, v1
	s_cbranch_vccnz .Lgb_acq
	s_sleep 1
	s_add_i32 s58, s58, 1
	s_cmp_lt_u32 s58, 0x40001
	s_cbranch_scc1 .Lgb_spin_loop
.Lgb_acq:
	s_waitcnt vmcnt(0) lgkmcnt(0)
	buffer_inv sc1
	s_waitcnt vmcnt(0)
